# PB1 dilated-attention softmax: cross-half max exchange only on the rescale path at 3 sites (on top of v25)
# baseline (speedup 1.0000x reference)
; #define LAS __attribute__((address_space(3)))
; #define MFMA32(a, b, c) __builtin_amdgcn_mfma_f32_32x32x16_bf16((a), (b), (c), 0, 0, 0)
; template <int D, int NM, int KSTR, int VSTR, bool QLDS, class BF> ...
;     ...
;         const LAS unsigned char* Kb = (m == 0 ? K0 : K1) + (32 * kk + r) * KSTR + h * 16;
;         v16f S;
; #pragma unroll
;         for (int i = 0; i < 16; ++i) S[i] = 0.f;
;         v8s kfa[D / 16];
; #pragma unroll
;         for (int ks = 0; ks < D / 16; ++ks) kfa[ks] = *(const LAS v8s*)(Kb + ks * 32);
;         __builtin_amdgcn_sched_barrier(0);
; #pragma unroll
;         for (int ks = 0; ks < D / 16; ++ks) { const v8s qf = QLDS ? *(const LAS v8s*)(qlds + (m * (D / 16) + ks) * 1024) : Q[m][ks]; S = MFMA32(kfa[ks], qf, S); }
;         __builtin_amdgcn_sched_barrier(0);
;         float tmax = NEGBIG;
; #pragma unroll
;         for (int i = 0; i < 16; ++i) { S[i] = S[i] * c1 + bias(i); tmax = fmaxf(tmax, S[i]); }
;         tmax = fmaxf(tmax, __shfl_xor(tmax, 32));
;         const float mo = st.m[m], mn = fmaxf(mo, tmax);
;         if (__any(mn > mo)) {
;             const float alpha = __builtin_amdgcn_exp2f(mo - mn);
;             st.l[m] *= alpha;
; #pragma unroll
;             for (int eb = 0; eb < 4; ++eb)
; #pragma unroll
;                 for (int i = 0; i < 16; ++i) st.O[m][eb][i] *= alpha;
;             st.m[m] = mn;
;         }
; __device__ __forceinline__ void dil_item(const Params& p, LAS unsigned char* lds, const int bitem) {
;     ...
;                 const int js = j0 + 32 * kk;
;                 if (js + 31 >= jq0 - 64 && js <= jq0 + 31 + 64) {
;                     const BiasBand bf{tab, js + 4 * h - jq};
.LBB0_172:
	s_and_saveexec_b64 s[18:19], s[10:11]
	s_cbranch_execz .LBB0_165
	v_subrev_u32_e32 v67, 33, v176
	v_cmp_ge_i32_e32 vcc, v67, v188
	v_cmp_le_i32_e64 s[38:39], v66, v189
	s_and_b64 s[10:11], vcc, s[38:39]
	s_and_saveexec_b64 s[20:21], s[10:11]
	s_cbranch_execz .LBB0_209
	v_add_u32_e32 v70, v190, v187
	ds_read_b128 v[66:69], v70
	ds_read_b128 v[198:201], v70 offset:32
	ds_read_b128 v[216:219], v70 offset:64
	ds_read_b128 v[220:223], v70 offset:96
	ds_read_b128 v[224:227], v70 offset:128
	ds_read_b128 v[228:231], v70 offset:160
	ds_read_b128 v[232:235], v70 offset:192
	ds_read_b128 v[236:239], v70 offset:224
	v_lshl_add_u64 v[178:179], v[174:175], 0, s[6:7]
	v_subrev_u32_e32 v197, 64, v178
	s_waitcnt lgkmcnt(7)
	v_mfma_f32_32x32x16_bf16 v[66:81], v[66:69], v[82:85], 0
	s_waitcnt lgkmcnt(6)
	v_mfma_f32_32x32x16_bf16 v[66:81], v[198:201], v[86:89], v[66:81]
	s_waitcnt lgkmcnt(5)
	v_mfma_f32_32x32x16_bf16 v[66:81], v[216:219], v[90:93], v[66:81]
	s_waitcnt lgkmcnt(4)
	v_mfma_f32_32x32x16_bf16 v[66:81], v[220:223], v[94:97], v[66:81]
	s_waitcnt lgkmcnt(3)
	v_mfma_f32_32x32x16_bf16 v[66:81], v[224:227], v[98:101], v[66:81]
	s_waitcnt lgkmcnt(2)
	v_mfma_f32_32x32x16_bf16 v[66:81], v[228:231], v[102:105], v[66:81]
	s_waitcnt lgkmcnt(1)
	v_mfma_f32_32x32x16_bf16 v[66:81], v[232:235], v[106:109], v[66:81]
	s_waitcnt lgkmcnt(0)
	v_mfma_f32_32x32x16_bf16 v[66:81], v[236:239], v[110:113], v[66:81]
	v_lshl_add_u32 v178, v197, 2, v147
	ds_read_b32 v179, v178 offset:256
	ds_read_b32 v177, v178 offset:260
	ds_read_b32 v198, v178 offset:264
	ds_read_b32 v197, v178 offset:268
	ds_read_b32 v200, v178 offset:288
	ds_read_b32 v199, v178 offset:292
	ds_read_b32 v202, v178 offset:296
	ds_read_b32 v201, v178 offset:300
	s_waitcnt lgkmcnt(4)
	ds_read_b32 v215, v178 offset:320
	ds_read_b32 v203, v178 offset:324
	ds_read_b32 v217, v178 offset:328
	ds_read_b32 v216, v178 offset:332
	ds_read_b32 v219, v178 offset:352
	ds_read_b32 v218, v178 offset:356
	ds_read_b32 v221, v178 offset:360
	ds_read_b32 v220, v178 offset:364
	s_waitcnt lgkmcnt(0)
	v_fmac_f32_e32 v179, 0x3e0293ee, v66
	v_fmac_f32_e32 v177, 0x3e0293ee, v67
	v_max3_f32 v66, v179, s15, v177
	v_fmac_f32_e32 v198, 0x3e0293ee, v68
	v_fmac_f32_e32 v197, 0x3e0293ee, v69
	v_max3_f32 v66, v66, v198, v197
	v_fmac_f32_e32 v200, 0x3e0293ee, v70
	v_fmac_f32_e32 v199, 0x3e0293ee, v71
	v_max3_f32 v66, v66, v200, v199
	v_fmac_f32_e32 v202, 0x3e0293ee, v72
	v_fmac_f32_e32 v201, 0x3e0293ee, v73
	v_max3_f32 v66, v66, v202, v201
	v_fmac_f32_e32 v215, 0x3e0293ee, v74
	v_fmac_f32_e32 v203, 0x3e0293ee, v75
	v_max3_f32 v66, v66, v215, v203
	v_fmac_f32_e32 v217, 0x3e0293ee, v76
	v_fmac_f32_e32 v216, 0x3e0293ee, v77
	v_max3_f32 v66, v66, v217, v216
	v_fmac_f32_e32 v219, 0x3e0293ee, v78
	v_fmac_f32_e32 v218, 0x3e0293ee, v79
	v_max3_f32 v66, v66, v219, v218
	v_fmac_f32_e32 v221, 0x3e0293ee, v80
	v_fmac_f32_e32 v220, 0x3e0293ee, v81
	v_max3_f32 v66, v66, v221, v220
	v_add_f32_e32 v67, 0x41000000, v193
	v_cmp_gt_f32_e32 vcc, v66, v67
	s_cbranch_vccz .Lpb1_skip6
	v_mov_b32_e32 v67, v66
	s_nop 1
	v_permlane32_swap_b32_e32 v67, v66
	v_max_f32_e32 v66, v66, v67
	v_add_f32_e32 v67, 0x41000000, v193
	v_cmp_gt_f32_e32 vcc, v66, v67
	s_nop 1
	v_cndmask_b32_e32 v66, v193, v66, vcc
	v_sub_f32_e32 v67, v193, v66
	v_exp_f32_e32 v68, v67
	v_mov_b32_e32 v193, v66
	v_mul_f32_e32 v194, v194, v68
	v_pk_mul_f32 v[64:65], v[64:65], v[68:69] op_sel_hi:[1,0]
	v_pk_mul_f32 v[62:63], v[62:63], v[68:69] op_sel_hi:[1,0]
	v_pk_mul_f32 v[60:61], v[60:61], v[68:69] op_sel_hi:[1,0]
	v_pk_mul_f32 v[58:59], v[58:59], v[68:69] op_sel_hi:[1,0]
	v_pk_mul_f32 v[56:57], v[56:57], v[68:69] op_sel_hi:[1,0]
	v_pk_mul_f32 v[54:55], v[54:55], v[68:69] op_sel_hi:[1,0]
	v_pk_mul_f32 v[52:53], v[52:53], v[68:69] op_sel_hi:[1,0]
	v_pk_mul_f32 v[50:51], v[50:51], v[68:69] op_sel_hi:[1,0]
	v_pk_mul_f32 v[48:49], v[48:49], v[68:69] op_sel_hi:[1,0]
	v_pk_mul_f32 v[46:47], v[46:47], v[68:69] op_sel_hi:[1,0]
	v_pk_mul_f32 v[44:45], v[44:45], v[68:69] op_sel_hi:[1,0]
	v_pk_mul_f32 v[42:43], v[42:43], v[68:69] op_sel_hi:[1,0]
	v_pk_mul_f32 v[40:41], v[40:41], v[68:69] op_sel_hi:[1,0]
	v_pk_mul_f32 v[38:39], v[38:39], v[68:69] op_sel_hi:[1,0]
	v_pk_mul_f32 v[36:37], v[36:37], v[68:69] op_sel_hi:[1,0]
	v_pk_mul_f32 v[34:35], v[34:35], v[68:69] op_sel_hi:[1,0]
	v_pk_mul_f32 v[32:33], v[32:33], v[68:69] op_sel_hi:[1,0]
	v_pk_mul_f32 v[30:31], v[30:31], v[68:69] op_sel_hi:[1,0]
	v_pk_mul_f32 v[28:29], v[28:29], v[68:69] op_sel_hi:[1,0]
	v_pk_mul_f32 v[26:27], v[26:27], v[68:69] op_sel_hi:[1,0]
	v_pk_mul_f32 v[24:25], v[24:25], v[68:69] op_sel_hi:[1,0]
	v_pk_mul_f32 v[22:23], v[22:23], v[68:69] op_sel_hi:[1,0]
	v_pk_mul_f32 v[20:21], v[20:21], v[68:69] op_sel_hi:[1,0]
	v_pk_mul_f32 v[18:19], v[18:19], v[68:69] op_sel_hi:[1,0]
	v_pk_mul_f32 v[16:17], v[16:17], v[68:69] op_sel_hi:[1,0]
	v_pk_mul_f32 v[14:15], v[14:15], v[68:69] op_sel_hi:[1,0]
	v_pk_mul_f32 v[12:13], v[12:13], v[68:69] op_sel_hi:[1,0]
	v_pk_mul_f32 v[10:11], v[10:11], v[68:69] op_sel_hi:[1,0]
	v_pk_mul_f32 v[8:9], v[8:9], v[68:69] op_sel_hi:[1,0]
	v_pk_mul_f32 v[6:7], v[6:7], v[68:69] op_sel_hi:[1,0]
	v_pk_mul_f32 v[4:5], v[4:5], v[68:69] op_sel_hi:[1,0]
	v_pk_mul_f32 v[2:3], v[2:3], v[68:69] op_sel_hi:[1,0]
	s_branch .LBB0_208
.Lpb1_skip6:
	v_mov_b32_e32 v66, v193

; #define LAS __attribute__((address_space(3)))
; #define MFMA32(a, b, c) __builtin_amdgcn_mfma_f32_32x32x16_bf16((a), (b), (c), 0, 0, 0)
; template <int D, int NM, int KSTR, int VSTR, bool QLDS, class BF> ...
;     ...
;         const LAS unsigned char* Kb = (m == 0 ? K0 : K1) + (32 * kk + r) * KSTR + h * 16;
;         v16f S;
; #pragma unroll
;         for (int i = 0; i < 16; ++i) S[i] = 0.f;
;         v8s kfa[D / 16];
; #pragma unroll
;         for (int ks = 0; ks < D / 16; ++ks) kfa[ks] = *(const LAS v8s*)(Kb + ks * 32);
;         __builtin_amdgcn_sched_barrier(0);
; #pragma unroll
;         for (int ks = 0; ks < D / 16; ++ks) { const v8s qf = QLDS ? *(const LAS v8s*)(qlds + (m * (D / 16) + ks) * 1024) : Q[m][ks]; S = MFMA32(kfa[ks], qf, S); }
;         __builtin_amdgcn_sched_barrier(0);
;         float tmax = NEGBIG;
; #pragma unroll
;         for (int i = 0; i < 16; ++i) { S[i] = S[i] * c1 + bias(i); tmax = fmaxf(tmax, S[i]); }
;         tmax = fmaxf(tmax, __shfl_xor(tmax, 32));
;         const float mo = st.m[m], mn = fmaxf(mo, tmax);
;         if (__any(mn > mo)) {
;             const float alpha = __builtin_amdgcn_exp2f(mo - mn);
;             st.l[m] *= alpha;
; #pragma unroll
;             for (int eb = 0; eb < 4; ++eb)
; #pragma unroll
;                 for (int i = 0; i < 16; ++i) st.O[m][eb][i] *= alpha;
;             st.m[m] = mn;
;         }
; __device__ __forceinline__ void mem_item(const Params& p, LAS unsigned char* lds, const int item, const int layer) {
;     ...
;     for (int t = 0; t < 4; ++t) {
;         __syncthreads();
;         *(LAS v4u*)dK = g0; *(LAS v4u*)(dK + 32 * 272) = g1; *(LAS v4u*)dV = g2; *(LAS v4u*)(dV + 32 * 320) = g3;
;         __syncthreads();
;         if (t + 1 < 4) { const bf16* nK = sK + (size_t)(t + 1) * 64 * 1024;
;             g0 = *(const v4u*)nK; g1 = *(const v4u*)(nK + 32 * 1024); g2 = *(const v4u*)(nK + 512); g3 = *(const v4u*)(nK + 32 * 1024 + 512); }
.LBB0_249:
	v_lshl_add_u64 v[66:67], v[138:139], 0, s[6:7]
	s_mov_b32 s11, 0x9820000
	v_add_co_u32_e32 v68, vcc, s11, v66
	s_mov_b32 s11, 0x9830000
	s_nop 0
	v_addc_co_u32_e32 v69, vcc, 0, v67, vcc
	v_add_u32_e32 v0, v136, v134
	v_add_co_u32_e32 v66, vcc, s11, v66
	s_barrier
	s_waitcnt vmcnt(3)
	ds_write_b128 v0, v[114:117]
	s_waitcnt vmcnt(1)
	ds_write_b128 v0, v[126:129] offset:8704
	ds_write_b128 v146, v[118:121] offset:17408
	s_waitcnt vmcnt(0)
	ds_write_b128 v146, v[122:125] offset:27648
	s_waitcnt lgkmcnt(0)
	s_barrier
	v_addc_co_u32_e32 v67, vcc, 0, v67, vcc
	global_load_dwordx4 v[114:117], v[68:69], off
	global_load_dwordx4 v[118:121], v[68:69], off offset:1024
	global_load_dwordx4 v[126:129], v[66:67], off
	global_load_dwordx4 v[122:125], v[66:67], off offset:1024
	ds_read_b128 v[66:69], v144
	ds_read_b128 v[148:151], v144 offset:32
	ds_read_b128 v[152:155], v144 offset:64
	ds_read_b128 v[156:159], v144 offset:96
	ds_read_b128 v[160:163], v144 offset:128
	ds_read_b128 v[174:177], v144 offset:160
	ds_read_b128 v[178:181], v144 offset:192
	ds_read_b128 v[182:185], v144 offset:224
	s_waitcnt lgkmcnt(7)
	v_mfma_f32_32x32x16_bf16 v[66:81], v[66:69], v[110:113], 0
	s_waitcnt lgkmcnt(6)
	v_mfma_f32_32x32x16_bf16 v[66:81], v[148:151], v[106:109], v[66:81]
	s_waitcnt lgkmcnt(5)
	v_mfma_f32_32x32x16_bf16 v[66:81], v[152:155], v[102:105], v[66:81]
	s_waitcnt lgkmcnt(4)
	v_mfma_f32_32x32x16_bf16 v[66:81], v[156:159], v[98:101], v[66:81]
	s_waitcnt lgkmcnt(3)
	v_mfma_f32_32x32x16_bf16 v[66:81], v[160:163], v[94:97], v[66:81]
	s_waitcnt lgkmcnt(2)
	v_mfma_f32_32x32x16_bf16 v[66:81], v[174:177], v[90:93], v[66:81]
	s_waitcnt lgkmcnt(1)
	v_mfma_f32_32x32x16_bf16 v[66:81], v[178:181], v[86:89], v[66:81]
	s_waitcnt lgkmcnt(0)
	v_mfma_f32_32x32x16_bf16 v[66:81], v[182:185], v[82:85], v[66:81]
	s_nop 11
	v_fma_f32 v155, v66, s14, 0
	v_fma_f32 v154, v67, s14, 0
	v_max3_f32 v66, v155, s15, v154
	v_fma_f32 v153, v68, s14, 0
	v_fma_f32 v152, v69, s14, 0
	v_max3_f32 v66, v66, v153, v152
	v_fma_f32 v151, v70, s14, 0
	v_fma_f32 v150, v71, s14, 0
	v_max3_f32 v66, v66, v151, v150
	v_fma_f32 v149, v72, s14, 0
	v_fma_f32 v148, v73, s14, 0
	v_max3_f32 v66, v66, v149, v148
	v_fma_f32 v74, v74, s14, 0
	v_fma_f32 v73, v75, s14, 0
	v_max3_f32 v66, v66, v74, v73
	v_fma_f32 v72, v76, s14, 0
	v_fma_f32 v71, v77, s14, 0
	v_max3_f32 v66, v66, v72, v71
	v_fma_f32 v70, v78, s14, 0
	v_fma_f32 v69, v79, s14, 0
	v_max3_f32 v67, v66, v70, v69
	v_fma_f32 v68, v80, s14, 0
	v_fma_f32 v66, v81, s14, 0
	v_max3_f32 v67, v67, v68, v66
	v_add_f32_e32 v75, 0x41000000, v145
	v_cmp_gt_f32_e32 vcc, v67, v75
	s_cbranch_vccz .Lpb1_skip4
	v_mov_b32_e32 v75, v67
	s_nop 1
	v_permlane32_swap_b32_e32 v75, v67
	v_max_f32_e32 v67, v67, v75
	v_add_f32_e32 v75, 0x41000000, v145
	v_cmp_gt_f32_e32 vcc, v67, v75
	s_nop 1
	v_cndmask_b32_e32 v67, v145, v67, vcc
	v_sub_f32_e32 v75, v145, v67
	v_exp_f32_e32 v76, v75
	v_mov_b32_e32 v145, v67
	v_mul_f32_e32 v147, v147, v76
	v_pk_mul_f32 v[64:65], v[64:65], v[76:77] op_sel_hi:[1,0]
	v_pk_mul_f32 v[62:63], v[62:63], v[76:77] op_sel_hi:[1,0]
	v_pk_mul_f32 v[60:61], v[60:61], v[76:77] op_sel_hi:[1,0]
	v_pk_mul_f32 v[58:59], v[58:59], v[76:77] op_sel_hi:[1,0]
	v_pk_mul_f32 v[56:57], v[56:57], v[76:77] op_sel_hi:[1,0]
	v_pk_mul_f32 v[54:55], v[54:55], v[76:77] op_sel_hi:[1,0]
	v_pk_mul_f32 v[52:53], v[52:53], v[76:77] op_sel_hi:[1,0]
	v_pk_mul_f32 v[50:51], v[50:51], v[76:77] op_sel_hi:[1,0]
	v_pk_mul_f32 v[48:49], v[48:49], v[76:77] op_sel_hi:[1,0]
	v_pk_mul_f32 v[46:47], v[46:47], v[76:77] op_sel_hi:[1,0]
	v_pk_mul_f32 v[44:45], v[44:45], v[76:77] op_sel_hi:[1,0]
	v_pk_mul_f32 v[42:43], v[42:43], v[76:77] op_sel_hi:[1,0]
	v_pk_mul_f32 v[40:41], v[40:41], v[76:77] op_sel_hi:[1,0]
	v_pk_mul_f32 v[38:39], v[38:39], v[76:77] op_sel_hi:[1,0]
	v_pk_mul_f32 v[36:37], v[36:37], v[76:77] op_sel_hi:[1,0]
	v_pk_mul_f32 v[34:35], v[34:35], v[76:77] op_sel_hi:[1,0]
	v_pk_mul_f32 v[32:33], v[32:33], v[76:77] op_sel_hi:[1,0]
	v_pk_mul_f32 v[30:31], v[30:31], v[76:77] op_sel_hi:[1,0]
	v_pk_mul_f32 v[28:29], v[28:29], v[76:77] op_sel_hi:[1,0]
	v_pk_mul_f32 v[26:27], v[26:27], v[76:77] op_sel_hi:[1,0]
	v_pk_mul_f32 v[24:25], v[24:25], v[76:77] op_sel_hi:[1,0]
	v_pk_mul_f32 v[22:23], v[22:23], v[76:77] op_sel_hi:[1,0]
	v_pk_mul_f32 v[20:21], v[20:21], v[76:77] op_sel_hi:[1,0]
	v_pk_mul_f32 v[18:19], v[18:19], v[76:77] op_sel_hi:[1,0]
	v_pk_mul_f32 v[16:17], v[16:17], v[76:77] op_sel_hi:[1,0]
	v_pk_mul_f32 v[14:15], v[14:15], v[76:77] op_sel_hi:[1,0]
	v_pk_mul_f32 v[12:13], v[12:13], v[76:77] op_sel_hi:[1,0]
	v_pk_mul_f32 v[10:11], v[10:11], v[76:77] op_sel_hi:[1,0]
	v_pk_mul_f32 v[8:9], v[8:9], v[76:77] op_sel_hi:[1,0]
	v_pk_mul_f32 v[6:7], v[6:7], v[76:77] op_sel_hi:[1,0]
	v_pk_mul_f32 v[4:5], v[4:5], v[76:77] op_sel_hi:[1,0]
	v_pk_mul_f32 v[2:3], v[2:3], v[76:77] op_sel_hi:[1,0]
	s_branch .LBB0_251
.Lpb1_skip4:
	v_mov_b32_e32 v67, v145

; #define LAS __attribute__((address_space(3)))
; #define MFMA32(a, b, c) __builtin_amdgcn_mfma_f32_32x32x16_bf16((a), (b), (c), 0, 0, 0)
; template <int D, int NM, int KSTR, int VSTR, bool QLDS, class BF> ...
;     ...
;         const LAS unsigned char* Kb = (m == 0 ? K0 : K1) + (32 * kk + r) * KSTR + h * 16;
;         v16f S;
; #pragma unroll
;         for (int i = 0; i < 16; ++i) S[i] = 0.f;
;         v8s kfa[D / 16];
; #pragma unroll
;         for (int ks = 0; ks < D / 16; ++ks) kfa[ks] = *(const LAS v8s*)(Kb + ks * 32);
;         __builtin_amdgcn_sched_barrier(0);
; #pragma unroll
;         for (int ks = 0; ks < D / 16; ++ks) { const v8s qf = QLDS ? *(const LAS v8s*)(qlds + (m * (D / 16) + ks) * 1024) : Q[m][ks]; S = MFMA32(kfa[ks], qf, S); }
;         __builtin_amdgcn_sched_barrier(0);
;         float tmax = NEGBIG;
; #pragma unroll
;         for (int i = 0; i < 16; ++i) { S[i] = S[i] * c1 + bias(i); tmax = fmaxf(tmax, S[i]); }
;         tmax = fmaxf(tmax, __shfl_xor(tmax, 32));
;         const float mo = st.m[m], mn = fmaxf(mo, tmax);
;         if (__any(mn > mo)) {
;             const float alpha = __builtin_amdgcn_exp2f(mo - mn);
;             st.l[m] *= alpha;
; #pragma unroll
;             for (int eb = 0; eb < 4; ++eb)
; #pragma unroll
;                 for (int i = 0; i < 16; ++i) st.O[m][eb][i] *= alpha;
;             st.m[m] = mn;
;         }
; __device__ __forceinline__ void mem_item(const Params& p, LAS unsigned char* lds, const int item, const int layer) {
;     ...
;         __syncthreads();
;         *(LAS v4u*)dK = g0; *(LAS v4u*)(dK + 32 * 272) = g1; *(LAS v4u*)dV = g2; *(LAS v4u*)(dV + 32 * 320) = g3;
;         __syncthreads();
.LBB0_253:
	s_barrier
	s_waitcnt vmcnt(3)
	ds_write_b128 v0, v[114:117]
	s_waitcnt vmcnt(1)
	ds_write_b128 v0, v[126:129] offset:8704
	ds_write_b128 v146, v[118:121] offset:17408
	s_waitcnt vmcnt(0)
	ds_write_b128 v146, v[122:125] offset:27648
	s_waitcnt lgkmcnt(0)
	s_barrier
	ds_read_b128 v[66:69], v144
	ds_read_b128 v[114:117], v144 offset:32
	ds_read_b128 v[118:121], v144 offset:64
	ds_read_b128 v[122:125], v144 offset:96
	ds_read_b128 v[126:129], v144 offset:128
	ds_read_b128 v[148:151], v144 offset:160
	ds_read_b128 v[152:155], v144 offset:192
	ds_read_b128 v[156:159], v144 offset:224
	s_waitcnt lgkmcnt(7)
	v_mfma_f32_32x32x16_bf16 v[66:81], v[66:69], v[110:113], 0
	s_waitcnt lgkmcnt(6)
	v_mfma_f32_32x32x16_bf16 v[66:81], v[114:117], v[106:109], v[66:81]
	s_waitcnt lgkmcnt(5)
	v_mfma_f32_32x32x16_bf16 v[66:81], v[118:121], v[102:105], v[66:81]
	s_waitcnt lgkmcnt(4)
	v_mfma_f32_32x32x16_bf16 v[66:81], v[122:125], v[98:101], v[66:81]
	s_waitcnt lgkmcnt(3)
	v_mfma_f32_32x32x16_bf16 v[66:81], v[126:129], v[94:97], v[66:81]
	s_waitcnt lgkmcnt(2)
	v_mfma_f32_32x32x16_bf16 v[66:81], v[148:151], v[90:93], v[66:81]
	s_waitcnt lgkmcnt(1)
	v_mfma_f32_32x32x16_bf16 v[66:81], v[152:155], v[86:89], v[66:81]
	s_waitcnt lgkmcnt(0)
	v_mfma_f32_32x32x16_bf16 v[66:81], v[156:159], v[82:85], v[66:81]
	s_nop 11
	v_fma_f32 v121, v66, s14, 0
	v_fma_f32 v120, v67, s14, 0
	v_max3_f32 v0, v121, s15, v120
	v_fma_f32 v119, v68, s14, 0
	v_fma_f32 v118, v69, s14, 0
	v_max3_f32 v0, v0, v119, v118
	v_fma_f32 v117, v70, s14, 0
	v_fma_f32 v116, v71, s14, 0
	v_max3_f32 v0, v0, v117, v116
	v_fma_f32 v115, v72, s14, 0
	v_fma_f32 v114, v73, s14, 0
	v_max3_f32 v0, v0, v115, v114
	v_fma_f32 v73, v74, s14, 0
	v_fma_f32 v72, v75, s14, 0
	v_max3_f32 v0, v0, v73, v72
	v_fma_f32 v71, v76, s14, 0
	v_fma_f32 v70, v77, s14, 0
	v_max3_f32 v0, v0, v71, v70
	v_fma_f32 v69, v78, s14, 0
	v_fma_f32 v68, v79, s14, 0
	v_max3_f32 v66, v0, v69, v68
	v_fma_f32 v67, v80, s14, 0
	v_fma_f32 v0, v81, s14, 0
	v_max3_f32 v66, v66, v67, v0
	v_add_f32_e32 v74, 0x41000000, v145
	v_cmp_gt_f32_e32 vcc, v66, v74
	s_cbranch_vccz .Lpb1_skip2
	v_mov_b32_e32 v74, v66
	s_nop 1
	v_permlane32_swap_b32_e32 v74, v66
	v_max_f32_e32 v66, v66, v74
	v_add_f32_e32 v74, 0x41000000, v145
	v_cmp_gt_f32_e32 vcc, v66, v74
	s_nop 1
	v_cndmask_b32_e32 v66, v145, v66, vcc
	v_sub_f32_e32 v74, v145, v66
	v_exp_f32_e32 v74, v74
	v_mov_b32_e32 v145, v66
	v_mul_f32_e32 v147, v147, v74
	v_pk_mul_f32 v[64:65], v[64:65], v[74:75] op_sel_hi:[1,0]
	v_pk_mul_f32 v[62:63], v[62:63], v[74:75] op_sel_hi:[1,0]
	v_pk_mul_f32 v[60:61], v[60:61], v[74:75] op_sel_hi:[1,0]
	v_pk_mul_f32 v[58:59], v[58:59], v[74:75] op_sel_hi:[1,0]
	v_pk_mul_f32 v[56:57], v[56:57], v[74:75] op_sel_hi:[1,0]
	v_pk_mul_f32 v[54:55], v[54:55], v[74:75] op_sel_hi:[1,0]
	v_pk_mul_f32 v[52:53], v[52:53], v[74:75] op_sel_hi:[1,0]
	v_pk_mul_f32 v[50:51], v[50:51], v[74:75] op_sel_hi:[1,0]
	v_pk_mul_f32 v[48:49], v[48:49], v[74:75] op_sel_hi:[1,0]
	v_pk_mul_f32 v[46:47], v[46:47], v[74:75] op_sel_hi:[1,0]
	v_pk_mul_f32 v[44:45], v[44:45], v[74:75] op_sel_hi:[1,0]
	v_pk_mul_f32 v[42:43], v[42:43], v[74:75] op_sel_hi:[1,0]
	v_pk_mul_f32 v[40:41], v[40:41], v[74:75] op_sel_hi:[1,0]
	v_pk_mul_f32 v[38:39], v[38:39], v[74:75] op_sel_hi:[1,0]
	v_pk_mul_f32 v[36:37], v[36:37], v[74:75] op_sel_hi:[1,0]
	v_pk_mul_f32 v[34:35], v[34:35], v[74:75] op_sel_hi:[1,0]
	v_pk_mul_f32 v[32:33], v[32:33], v[74:75] op_sel_hi:[1,0]
	v_pk_mul_f32 v[30:31], v[30:31], v[74:75] op_sel_hi:[1,0]
	v_pk_mul_f32 v[28:29], v[28:29], v[74:75] op_sel_hi:[1,0]
	v_pk_mul_f32 v[26:27], v[26:27], v[74:75] op_sel_hi:[1,0]
	v_pk_mul_f32 v[24:25], v[24:25], v[74:75] op_sel_hi:[1,0]
	v_pk_mul_f32 v[22:23], v[22:23], v[74:75] op_sel_hi:[1,0]
	v_pk_mul_f32 v[20:21], v[20:21], v[74:75] op_sel_hi:[1,0]
	v_pk_mul_f32 v[18:19], v[18:19], v[74:75] op_sel_hi:[1,0]
	v_pk_mul_f32 v[16:17], v[16:17], v[74:75] op_sel_hi:[1,0]
	v_pk_mul_f32 v[14:15], v[14:15], v[74:75] op_sel_hi:[1,0]
	v_pk_mul_f32 v[12:13], v[12:13], v[74:75] op_sel_hi:[1,0]
	v_pk_mul_f32 v[10:11], v[10:11], v[74:75] op_sel_hi:[1,0]
	v_pk_mul_f32 v[8:9], v[8:9], v[74:75] op_sel_hi:[1,0]
	v_pk_mul_f32 v[6:7], v[6:7], v[74:75] op_sel_hi:[1,0]
	v_pk_mul_f32 v[4:5], v[4:5], v[74:75] op_sel_hi:[1,0]
	v_pk_mul_f32 v[2:3], v[2:3], v[74:75] op_sel_hi:[1,0]
	s_branch .LBB0_255
.Lpb1_skip2:
	v_mov_b32_e32 v66, v145
